# NSA unit assignment rebalanced: third unit of each workgroup is query block 191-j instead of 128+j
# speedup vs baseline: 1.0017x; 1.0017x over previous
; #define LAS __attribute__((address_space(3)))
; #define WAVE_F (__builtin_amdgcn_readfirstlane(TID_F >> 6))
; __device__ __forceinline__ void nsa_unit(const Params& p, int bg, int jq, LAS unsigned char* lds, int wave, int lane, bool build_lut) {
;     ...
;     const int tq0 = 64 * jq + 8 * wave, tq = tq0 + ql;
;     const size_t tok = (size_t)b * S + tq;
;     if (build_lut) {
;         for (int e = lane; e < 4 * 129; e += 64) {
;             const int rr = e / 129, n = e % 129;
;             int bk = n;
;             if (n >= 16) bk = 16 + (n >= 19) + (n >= 21) + (n >= 24) + (n >= 27) + (n >= 31) + (n >= 35) + (n >= 40) + (n >= 46) + (n >= 52) + (n >= 59) + (n >= 67) + (n >= 77) + (n >= 87) + (n >= 99) + (n >= 113);
;             lut[rr * 132 + n] = relb[bk * 8 + g * 4 + rr] * LOG2E;
;         }
;     }
; #pragma unroll
;     for (int e = 0; e < 8; ++e) *(LAS f32x4*)(imp + 4 * (lane + 64 * e)) = (f32x4){0.f, 0.f, 0.f, 0.f};
;     {
;         const int k = lane & 7; unsigned w = 0u;
;         if (k == 0) w |= 1u;
;         if ((jq >> 5) == k) w |= 1u << (jq & 31);
;         if (jq >= 1 && ((jq - 1) >> 5) == k) w |= 1u << ((jq - 1) & 31);
;         selw[lane] = w;
;     }
;     asm volatile("s_waitcnt lgkmcnt(0)" ::: "memory");
;     __builtin_amdgcn_wave_barrier();
;     const LAS float* lutr = lut + r * 132;
;     const float lutfar = lutr[128];
;     bf16x8 qf[4];
; #pragma unroll
;     for (int ks = 0; ks < 4; ++ks) qf[ks] = *(const bf16x8*)(qb + tok * 512 + (g * 4 + r) * 64 + ks * 16 + h * 8);
;     const float g0 = gates[tok * 24 + (g * 4 + r) * 3 + 0], g1 = gates[tok * 24 + (g * 4 + r) * 3 + 1], g2 = gates[tok * 24 + (g * 4 + r) * 3 + 2];
;     f32x16 oa0, oa1;
;     bf16x8 kf[4], kn[4], vf[2][2];
;     {
;         const int jmaxw = (tq0 + 7 - 31) >> 4;
;         const int ntile = (jmaxw >= 0) ? (jmaxw >> 5) + 1 : 0;
;         float m = -1e30f, l = 0.f;
;         if (ntile > 0) load_k(kn, kcmp, lane);
; __global__ void __launch_bounds__(NTHREADS, 2) fwd_megakernel(Params p) {
;     ...
;                     const int x = bx & 7, y = bx >> 3, bg = x >> 1, j = (x & 1) * 32 + y;
;                     for (int i = 0; i < 4; ++i) {
;                         const int jq = (i >> 1) * 128 + ((i & 1) ? (127 - j) : j);
;                         nsa_unit(p, bg, jq, lds, WAVE_F, LANE_F, i == 0);
.LBB0_1051:
	s_or_b64 exec, exec, s[4:5]
	s_lshl_b32 s4, s26, 6
	s_and_b32 s28, s4, 0xffffe000
	s_lshl_b32 s4, s27, 6
	s_and_b32 s4, s4, 0x80
	s_bitcmp0_b32 s27, 0
	v_readlane_b32 s5, v253, 17
	v_readlane_b32 s6, v253, 18
	s_cselect_b32 s29, s5, s6
	s_cmp_lg_u32 s27, 2
	s_cbranch_scc1 .Ljq_keep
	s_sub_i32 s29, 63, s29
.Ljq_keep:
	s_add_i32 s20, s29, s4
	s_waitcnt lgkmcnt(0)
	s_add_u32 s16, s14, 0xa900000
	s_addc_u32 s17, s15, 0
	v_readlane_b32 s4, v253, 56
	s_add_u32 s4, s14, s4
	s_addc_u32 s5, s15, 0
	s_add_u32 s6, s4, 0x14300000
	s_addc_u32 s7, s5, 0
	s_lshl_b32 s4, s20, 6
	s_lshl_b32 s30, s12, 3
	v_bfe_u32 v158, v145, 2, 3
	s_add_i32 s31, s30, s4
	s_add_i32 s34, s18, 0
	v_or_b32_e32 v2, s31, v158
	s_ashr_i32 s8, s20, 5
	s_lshl_b32 s9, 1, s29
	v_ashrrev_i32_e32 v3, 31, v2
	v_and_b32_e32 v118, 7, v145
	s_cmp_gt_i32 s20, 0
	v_lshl_add_u64 v[182:183], v[2:3], 0, s[90:91]
	s_mov_b32 s73, s72
	v_mov_b32_e32 v3, s9
	v_cmp_eq_u32_e32 vcc, s8, v118
	s_cselect_b64 s[8:9], -1, 0
	s_add_i32 s10, s20, -1
	v_lshlrev_b32_e32 v114, 4, v145
	s_mov_b32 s74, s72
	s_mov_b32 s75, s72
	v_mov_b64_e32 v[4:5], s[72:73]
	s_lshr_b32 s11, s10, 5
	v_add_u32_e32 v2, s34, v114
	v_mov_b64_e32 v[6:7], s[74:75]
	v_cndmask_b32_e32 v3, 0, v3, vcc
	v_cmp_eq_u32_e32 vcc, s11, v118
	s_lshl_b32 s10, 1, s10
	ds_write_b128 v2, v[4:7]
	ds_write_b128 v2, v[4:7] offset:1024
	ds_write_b128 v2, v[4:7] offset:2048
	ds_write_b128 v2, v[4:7] offset:3072
	ds_write_b128 v2, v[4:7] offset:4096
	ds_write_b128 v2, v[4:7] offset:5120
	ds_write_b128 v2, v[4:7] offset:6144
	ds_write_b128 v2, v[4:7] offset:7168
	v_cmp_eq_u32_e64 s[4:5], 0, v118
	v_mov_b32_e32 v4, s10
	s_and_b64 vcc, s[8:9], vcc
	v_cndmask_b32_e64 v2, 0, 1, s[4:5]
	v_cndmask_b32_e32 v4, 0, v4, vcc
	v_or3_b32 v2, v3, v2, v4
	v_lshl_add_u32 v159, v145, 2, s34
	v_ashrrev_i32_e32 v179, 5, v145
	v_and_b32_e32 v1, 3, v145
	ds_write_b32 v159, v2 offset:8192
	v_lshlrev_b64 v[2:3], 10, v[182:183]
	v_readlane_b32 s8, v253, 57
	v_lshl_add_u64 v[140:141], s[16:17], 0, v[2:3]
	v_mov_b32_e32 v3, v0
	v_lshl_or_b32 v2, v1, 7, s8
	v_lshlrev_b32_e32 v142, 3, v179
	v_lshl_add_u64 v[2:3], v[140:141], 0, v[2:3]
	v_ashrrev_i32_e32 v143, 31, v142
	v_lshl_add_u64 v[2:3], v[142:143], 1, v[2:3]
	s_waitcnt lgkmcnt(0)
	global_load_dwordx4 v[66:69], v[2:3], off
	global_load_dwordx4 v[70:73], v[2:3], off offset:32
	global_load_dwordx4 v[74:77], v[2:3], off offset:64
	global_load_dwordx4 v[78:81], v[2:3], off offset:96
	v_or_b32_e32 v115, s3, v1
	v_mov_b64_e32 v[2:3], s[14:15]
	s_movk_i32 s10, 0x60
	v_mul_u32_u24_e32 v4, 3, v115
	v_mad_u64_u32 v[2:3], s[8:9], v182, s10, v[2:3]
	v_mad_i32_i24 v3, v183, s10, v3
	v_lshlrev_b32_e32 v4, 2, v4
	v_mov_b32_e32 v5, v0
	v_lshl_add_u64 v[2:3], v[2:3], 0, v[4:5]
	v_add_co_u32_e32 v2, vcc, 0x13b00000, v2
	s_movk_i32 s8, 0x210
	s_nop 0
	v_addc_co_u32_e32 v3, vcc, 0, v3, vcc
	global_load_dwordx3 v[176:178], v[2:3], off
	v_mov_b32_e32 v2, s34
	v_mad_u32_u24 v231, v1, s8, v2
	s_sub_i32 s8, s31, 24
	s_lshr_b32 s8, s8, 9
	ds_read_b32 v184, v231 offset:8960
	s_add_i32 s12, s8, 1
	s_cmp_gt_i32 s31, 23
	s_cselect_b64 s[8:9], -1, 0
	s_and_b64 s[10:11], s[8:9], exec
	s_cselect_b32 s21, s12, 0
	s_cmp_lt_i32 s31, 24
	s_cbranch_scc1 .LBB0_1092
	v_lshlrev_b32_e32 v2, 3, v145
	v_ashrrev_i32_e32 v3, 31, v2
	v_lshlrev_b64 v[18:19], 1, v[2:3]
	v_lshl_add_u64 v[14:15], s[6:7], 0, v[18:19]
	global_load_dwordx4 v[2:5], v[14:15], off
	global_load_dwordx4 v[6:9], v[14:15], off offset:1024
	global_load_dwordx4 v[10:13], v[14:15], off offset:2048
	s_nop 0
	global_load_dwordx4 v[14:17], v[14:15], off offset:3072
	s_lshl_b32 s10, s29, 6
	s_add_i32 s10, s28, s10
	s_add_i32 s11, s10, s30
	s_sub_i32 s11, s11, 24
	s_lshr_b32 s12, s11, 9
	v_add_u32_e32 v21, s10, v158
	s_sub_i32 s13, s10, 31
	v_readlane_b32 s10, v253, 52
	s_add_u32 s10, s14, s10
	v_lshlrev_b32_e32 v20, 6, v179
	s_addc_u32 s11, s15, 0
	s_waitcnt lgkmcnt(0)
	v_mov_b32_e32 v185, v184
	s_waitcnt vmcnt(9)
	v_mov_b32_e32 v50, v184
	v_mov_b32_e32 v51, v184
	v_mov_b32_e32 v52, v184
	v_mov_b32_e32 v53, v184
	v_mov_b32_e32 v54, v184
	v_mov_b32_e32 v55, v184
	v_mov_b32_e32 v56, v184
	v_mov_b32_e32 v57, v184
	v_mov_b32_e32 v58, v184
	v_mov_b32_e32 v59, v184
	v_mov_b32_e32 v60, v184
	v_mov_b32_e32 v61, v184
	v_mov_b32_e32 v62, v184
	v_mov_b32_e32 v63, v184
	v_sub_u32_e32 v82, v21, v20
	v_lshl_add_u64 v[64:65], s[10:11], 0, v[18:19]
	v_mov_b32_e32 v83, 0
	v_mov_b32_e32 v84, 0xf149f2ca
	s_mov_b32 s19, -1
	s_waitcnt vmcnt(3)
	v_mov_b64_e32 v[36:37], v[4:5]
	s_waitcnt vmcnt(2)
	v_mov_b64_e32 v[40:41], v[8:9]
	s_waitcnt vmcnt(1)
	v_mov_b64_e32 v[44:45], v[12:13]
	s_waitcnt vmcnt(0)
	v_mov_b64_e32 v[48:49], v[16:17]
	v_mov_b64_e32 v[34:35], v[2:3]
	v_mov_b64_e32 v[38:39], v[6:7]
	v_mov_b64_e32 v[42:43], v[10:11]
	v_mov_b64_e32 v[46:47], v[14:15]
	s_add_i32 s10, s19, 2
	s_cmp_lt_u32 s10, s21
	s_cbranch_scc0 .LBB0_1055
	s_branch .LBB0_1054
